# v23 + isel histogram address chains issued two keys at a time through separate temporaries
# baseline (speedup 1.0000x reference)
.LBB0_479:
	s_cmpk_gt_i32 s29, 0xff
	s_cbranch_scc0 .LBB0_512
	s_mov_b32 s72, s73
	s_mov_b32 s74, s73
	s_mov_b32 s75, s73
	v_mov_b64_e32 v[68:69], s[72:73]
	v_lshl_add_u32 v2, v221, 4, s34
	v_mov_b64_e32 v[70:71], s[74:75]
	ds_write_b128 v2, v[68:71]
	ds_write_b128 v2, v[68:71] offset:1024
	ds_write_b128 v2, v[68:71] offset:2048
	ds_write_b128 v2, v[68:71] offset:3072
	ds_write_b128 v2, v[68:71] offset:4096
	ds_write_b128 v2, v[68:71] offset:5120
	ds_write_b128 v2, v[68:71] offset:6144
	ds_write_b128 v2, v[68:71] offset:7168
	ds_write_b128 v2, v[68:71] offset:8192
	ds_write_b128 v2, v[68:71] offset:9216
	ds_write_b128 v2, v[68:71] offset:10240
	ds_write_b128 v2, v[68:71] offset:11264
	ds_write_b128 v2, v[68:71] offset:12288
	ds_write_b128 v2, v[68:71] offset:13312
	ds_write_b128 v2, v[68:71] offset:14336
	ds_write_b128 v2, v[68:71] offset:15360
	s_and_b64 vcc, exec, s[30:31]
	s_cbranch_vccz .LBB0_482
	s_waitcnt lgkmcnt(14)
	v_cmp_eq_u32_e32 vcc, 0, v4
	v_cmp_eq_u32_e64 s[98:99], 0, v0
	v_lshrrev_b32_e32 v2, 20, v4
	v_lshrrev_b32_e32 v3, 20, v0
	v_cndmask_b32_e32 v2, v2, v221, vcc
	v_cndmask_b32_e64 v3, v3, v221, s[98:99]
	v_lshl_add_u32 v2, v2, 2, s34
	v_lshl_add_u32 v3, v3, 2, s34
	ds_add_u32 v2, v213
	ds_add_u32 v3, v213
	v_cmp_eq_u32_e32 vcc, 0, v6
	v_cmp_eq_u32_e64 s[98:99], 0, v5
	v_lshrrev_b32_e32 v2, 20, v6
	v_lshrrev_b32_e32 v3, 20, v5
	v_cndmask_b32_e32 v2, v2, v221, vcc
	v_cndmask_b32_e64 v3, v3, v221, s[98:99]
	v_lshl_add_u32 v2, v2, 2, s34
	v_lshl_add_u32 v3, v3, 2, s34
	ds_add_u32 v2, v213
	ds_add_u32 v3, v213
	v_cmp_eq_u32_e32 vcc, 0, v8
	v_cmp_eq_u32_e64 s[98:99], 0, v7
	v_lshrrev_b32_e32 v2, 20, v8
	v_lshrrev_b32_e32 v3, 20, v7
	v_cndmask_b32_e32 v2, v2, v221, vcc
	v_cndmask_b32_e64 v3, v3, v221, s[98:99]
	v_lshl_add_u32 v2, v2, 2, s34
	v_lshl_add_u32 v3, v3, 2, s34
	ds_add_u32 v2, v213
	ds_add_u32 v3, v213
	v_cmp_eq_u32_e32 vcc, 0, v10
	v_cmp_eq_u32_e64 s[98:99], 0, v9
	v_lshrrev_b32_e32 v2, 20, v10
	v_lshrrev_b32_e32 v3, 20, v9
	v_cndmask_b32_e32 v2, v2, v221, vcc
	v_cndmask_b32_e64 v3, v3, v221, s[98:99]
	v_lshl_add_u32 v2, v2, 2, s34
	v_lshl_add_u32 v3, v3, 2, s34
	ds_add_u32 v2, v213
	ds_add_u32 v3, v213
.LBB0_482:
	v_cndmask_b32_e64 v2, 0, 1, s[4:5]
	v_cmp_ne_u32_e64 s[0:1], 1, v2
	s_andn2_b64 vcc, exec, s[4:5]
	s_cbranch_vccnz .LBB0_484
	s_waitcnt lgkmcnt(14)
	v_cmp_eq_u32_e32 vcc, 0, v12
	v_cmp_eq_u32_e64 s[98:99], 0, v11
	v_lshrrev_b32_e32 v2, 20, v12
	v_lshrrev_b32_e32 v3, 20, v11
	v_cndmask_b32_e32 v2, v2, v221, vcc
	v_cndmask_b32_e64 v3, v3, v221, s[98:99]
	v_lshl_add_u32 v2, v2, 2, s34
	v_lshl_add_u32 v3, v3, 2, s34
	ds_add_u32 v2, v213
	ds_add_u32 v3, v213
	v_cmp_eq_u32_e32 vcc, 0, v14
	v_cmp_eq_u32_e64 s[98:99], 0, v13
	v_lshrrev_b32_e32 v2, 20, v14
	v_lshrrev_b32_e32 v3, 20, v13
	v_cndmask_b32_e32 v2, v2, v221, vcc
	v_cndmask_b32_e64 v3, v3, v221, s[98:99]
	v_lshl_add_u32 v2, v2, 2, s34
	v_lshl_add_u32 v3, v3, 2, s34
	ds_add_u32 v2, v213
	ds_add_u32 v3, v213
	v_cmp_eq_u32_e32 vcc, 0, v16
	v_cmp_eq_u32_e64 s[98:99], 0, v15
	v_lshrrev_b32_e32 v2, 20, v16
	v_lshrrev_b32_e32 v3, 20, v15
	v_cndmask_b32_e32 v2, v2, v221, vcc
	v_cndmask_b32_e64 v3, v3, v221, s[98:99]
	v_lshl_add_u32 v2, v2, 2, s34
	v_lshl_add_u32 v3, v3, 2, s34
	ds_add_u32 v2, v213
	ds_add_u32 v3, v213
	v_cmp_eq_u32_e32 vcc, 0, v18
	v_cmp_eq_u32_e64 s[98:99], 0, v17
	v_lshrrev_b32_e32 v2, 20, v18
	v_lshrrev_b32_e32 v3, 20, v17
	v_cndmask_b32_e32 v2, v2, v221, vcc
	v_cndmask_b32_e64 v3, v3, v221, s[98:99]
	v_lshl_add_u32 v2, v2, 2, s34
	v_lshl_add_u32 v3, v3, 2, s34
	ds_add_u32 v2, v213
	ds_add_u32 v3, v213

.LBB0_490:
	s_waitcnt lgkmcnt(14)
	v_cmp_eq_u32_e32 vcc, 0, v60
	v_cmp_eq_u32_e64 s[98:99], 0, v59
	v_lshrrev_b32_e32 v2, 20, v60
	v_lshrrev_b32_e32 v3, 20, v59
	v_cndmask_b32_e32 v2, v2, v221, vcc
	v_cndmask_b32_e64 v3, v3, v221, s[98:99]
	v_lshl_add_u32 v2, v2, 2, s34
	v_lshl_add_u32 v3, v3, 2, s34
	ds_add_u32 v2, v213
	ds_add_u32 v3, v213
	v_cmp_eq_u32_e32 vcc, 0, v62
	v_cmp_eq_u32_e64 s[98:99], 0, v61
	v_lshrrev_b32_e32 v2, 20, v62
	v_lshrrev_b32_e32 v3, 20, v61
	v_cndmask_b32_e32 v2, v2, v221, vcc
	v_cndmask_b32_e64 v3, v3, v221, s[98:99]
	v_lshl_add_u32 v2, v2, 2, s34
	v_lshl_add_u32 v3, v3, 2, s34
	ds_add_u32 v2, v213
	ds_add_u32 v3, v213
	v_cmp_eq_u32_e32 vcc, 0, v64
	v_cmp_eq_u32_e64 s[98:99], 0, v63
	v_lshrrev_b32_e32 v2, 20, v64
	v_lshrrev_b32_e32 v3, 20, v63
	v_cndmask_b32_e32 v2, v2, v221, vcc
	v_cndmask_b32_e64 v3, v3, v221, s[98:99]
	v_lshl_add_u32 v2, v2, 2, s34
	v_lshl_add_u32 v3, v3, 2, s34
	ds_add_u32 v2, v213
	ds_add_u32 v3, v213
	v_cmp_eq_u32_e32 vcc, 0, v66
	v_cmp_eq_u32_e64 s[98:99], 0, v65
	v_lshrrev_b32_e32 v2, 20, v66
	v_lshrrev_b32_e32 v3, 20, v65
	v_cndmask_b32_e32 v2, v2, v221, vcc
	v_cndmask_b32_e64 v3, v3, v221, s[98:99]
	v_lshl_add_u32 v2, v2, 2, s34
	v_lshl_add_u32 v3, v3, 2, s34
	ds_add_u32 v2, v213
	ds_add_u32 v3, v213

.LBB0_515:
	s_waitcnt lgkmcnt(14)
	v_cmp_eq_u32_e32 vcc, 0, v20
	v_cmp_eq_u32_e64 s[98:99], 0, v19
	v_lshrrev_b32_e32 v2, 20, v20
	v_lshrrev_b32_e32 v3, 20, v19
	v_cndmask_b32_e32 v2, v2, v221, vcc
	v_cndmask_b32_e64 v3, v3, v221, s[98:99]
	v_lshl_add_u32 v2, v2, 2, s34
	v_lshl_add_u32 v3, v3, 2, s34
	ds_add_u32 v2, v213
	ds_add_u32 v3, v213
	v_cmp_eq_u32_e32 vcc, 0, v22
	v_cmp_eq_u32_e64 s[98:99], 0, v21
	v_lshrrev_b32_e32 v2, 20, v22
	v_lshrrev_b32_e32 v3, 20, v21
	v_cndmask_b32_e32 v2, v2, v221, vcc
	v_cndmask_b32_e64 v3, v3, v221, s[98:99]
	v_lshl_add_u32 v2, v2, 2, s34
	v_lshl_add_u32 v3, v3, 2, s34
	ds_add_u32 v2, v213
	ds_add_u32 v3, v213
	v_cmp_eq_u32_e32 vcc, 0, v24
	v_cmp_eq_u32_e64 s[98:99], 0, v23
	v_lshrrev_b32_e32 v2, 20, v24
	v_lshrrev_b32_e32 v3, 20, v23
	v_cndmask_b32_e32 v2, v2, v221, vcc
	v_cndmask_b32_e64 v3, v3, v221, s[98:99]
	v_lshl_add_u32 v2, v2, 2, s34
	v_lshl_add_u32 v3, v3, 2, s34
	ds_add_u32 v2, v213
	ds_add_u32 v3, v213
	v_cmp_eq_u32_e32 vcc, 0, v26
	v_cmp_eq_u32_e64 s[98:99], 0, v25
	v_lshrrev_b32_e32 v2, 20, v26
	v_lshrrev_b32_e32 v3, 20, v25
	v_cndmask_b32_e32 v2, v2, v221, vcc
	v_cndmask_b32_e64 v3, v3, v221, s[98:99]
	v_lshl_add_u32 v2, v2, 2, s34
	v_lshl_add_u32 v3, v3, 2, s34
	ds_add_u32 v2, v213
	ds_add_u32 v3, v213
	v_cndmask_b32_e64 v2, 0, 1, s[6:7]
	v_cmp_ne_u32_e64 s[4:5], 1, v2
	s_andn2_b64 vcc, exec, s[6:7]
	s_cbranch_vccnz .LBB0_486
.LBB0_516:
	s_waitcnt lgkmcnt(14)
	v_cmp_eq_u32_e32 vcc, 0, v28
	v_cmp_eq_u32_e64 s[98:99], 0, v27
	v_lshrrev_b32_e32 v2, 20, v28
	v_lshrrev_b32_e32 v3, 20, v27
	v_cndmask_b32_e32 v2, v2, v221, vcc
	v_cndmask_b32_e64 v3, v3, v221, s[98:99]
	v_lshl_add_u32 v2, v2, 2, s34
	v_lshl_add_u32 v3, v3, 2, s34
	ds_add_u32 v2, v213
	ds_add_u32 v3, v213
	v_cmp_eq_u32_e32 vcc, 0, v30
	v_cmp_eq_u32_e64 s[98:99], 0, v29
	v_lshrrev_b32_e32 v2, 20, v30
	v_lshrrev_b32_e32 v3, 20, v29
	v_cndmask_b32_e32 v2, v2, v221, vcc
	v_cndmask_b32_e64 v3, v3, v221, s[98:99]
	v_lshl_add_u32 v2, v2, 2, s34
	v_lshl_add_u32 v3, v3, 2, s34
	ds_add_u32 v2, v213
	ds_add_u32 v3, v213
	v_cmp_eq_u32_e32 vcc, 0, v32
	v_cmp_eq_u32_e64 s[98:99], 0, v31
	v_lshrrev_b32_e32 v2, 20, v32
	v_lshrrev_b32_e32 v3, 20, v31
	v_cndmask_b32_e32 v2, v2, v221, vcc
	v_cndmask_b32_e64 v3, v3, v221, s[98:99]
	v_lshl_add_u32 v2, v2, 2, s34
	v_lshl_add_u32 v3, v3, 2, s34
	ds_add_u32 v2, v213
	ds_add_u32 v3, v213
	v_cmp_eq_u32_e32 vcc, 0, v34
	v_cmp_eq_u32_e64 s[98:99], 0, v33
	v_lshrrev_b32_e32 v2, 20, v34
	v_lshrrev_b32_e32 v3, 20, v33
	v_cndmask_b32_e32 v2, v2, v221, vcc
	v_cndmask_b32_e64 v3, v3, v221, s[98:99]
	v_lshl_add_u32 v2, v2, 2, s34
	v_lshl_add_u32 v3, v3, 2, s34
	ds_add_u32 v2, v213
	ds_add_u32 v3, v213
	v_cndmask_b32_e64 v2, 0, 1, s[8:9]
	v_cmp_ne_u32_e64 s[6:7], 1, v2
	s_andn2_b64 vcc, exec, s[8:9]
	s_cbranch_vccnz .LBB0_487
.LBB0_517:
	s_waitcnt lgkmcnt(14)
	v_cmp_eq_u32_e32 vcc, 0, v36
	v_cmp_eq_u32_e64 s[98:99], 0, v35
	v_lshrrev_b32_e32 v2, 20, v36
	v_lshrrev_b32_e32 v3, 20, v35
	v_cndmask_b32_e32 v2, v2, v221, vcc
	v_cndmask_b32_e64 v3, v3, v221, s[98:99]
	v_lshl_add_u32 v2, v2, 2, s34
	v_lshl_add_u32 v3, v3, 2, s34
	ds_add_u32 v2, v213
	ds_add_u32 v3, v213
	v_cmp_eq_u32_e32 vcc, 0, v38
	v_cmp_eq_u32_e64 s[98:99], 0, v37
	v_lshrrev_b32_e32 v2, 20, v38
	v_lshrrev_b32_e32 v3, 20, v37
	v_cndmask_b32_e32 v2, v2, v221, vcc
	v_cndmask_b32_e64 v3, v3, v221, s[98:99]
	v_lshl_add_u32 v2, v2, 2, s34
	v_lshl_add_u32 v3, v3, 2, s34
	ds_add_u32 v2, v213
	ds_add_u32 v3, v213
	v_cmp_eq_u32_e32 vcc, 0, v40
	v_cmp_eq_u32_e64 s[98:99], 0, v39
	v_lshrrev_b32_e32 v2, 20, v40
	v_lshrrev_b32_e32 v3, 20, v39
	v_cndmask_b32_e32 v2, v2, v221, vcc
	v_cndmask_b32_e64 v3, v3, v221, s[98:99]
	v_lshl_add_u32 v2, v2, 2, s34
	v_lshl_add_u32 v3, v3, 2, s34
	ds_add_u32 v2, v213
	ds_add_u32 v3, v213
	v_cmp_eq_u32_e32 vcc, 0, v42
	v_cmp_eq_u32_e64 s[98:99], 0, v41
	v_lshrrev_b32_e32 v2, 20, v42
	v_lshrrev_b32_e32 v3, 20, v41
	v_cndmask_b32_e32 v2, v2, v221, vcc
	v_cndmask_b32_e64 v3, v3, v221, s[98:99]
	v_lshl_add_u32 v2, v2, 2, s34
	v_lshl_add_u32 v3, v3, 2, s34
	ds_add_u32 v2, v213
	ds_add_u32 v3, v213
	v_cndmask_b32_e64 v2, 0, 1, s[10:11]
	v_cmp_ne_u32_e64 s[8:9], 1, v2
	s_andn2_b64 vcc, exec, s[10:11]
	s_cbranch_vccnz .LBB0_488
.LBB0_518:
	s_waitcnt lgkmcnt(14)
	v_cmp_eq_u32_e32 vcc, 0, v44
	v_cmp_eq_u32_e64 s[98:99], 0, v43
	v_lshrrev_b32_e32 v2, 20, v44
	v_lshrrev_b32_e32 v3, 20, v43
	v_cndmask_b32_e32 v2, v2, v221, vcc
	v_cndmask_b32_e64 v3, v3, v221, s[98:99]
	v_lshl_add_u32 v2, v2, 2, s34
	v_lshl_add_u32 v3, v3, 2, s34
	ds_add_u32 v2, v213
	ds_add_u32 v3, v213
	v_cmp_eq_u32_e32 vcc, 0, v46
	v_cmp_eq_u32_e64 s[98:99], 0, v45
	v_lshrrev_b32_e32 v2, 20, v46
	v_lshrrev_b32_e32 v3, 20, v45
	v_cndmask_b32_e32 v2, v2, v221, vcc
	v_cndmask_b32_e64 v3, v3, v221, s[98:99]
	v_lshl_add_u32 v2, v2, 2, s34
	v_lshl_add_u32 v3, v3, 2, s34
	ds_add_u32 v2, v213
	ds_add_u32 v3, v213
	v_cmp_eq_u32_e32 vcc, 0, v48
	v_cmp_eq_u32_e64 s[98:99], 0, v47
	v_lshrrev_b32_e32 v2, 20, v48
	v_lshrrev_b32_e32 v3, 20, v47
	v_cndmask_b32_e32 v2, v2, v221, vcc
	v_cndmask_b32_e64 v3, v3, v221, s[98:99]
	v_lshl_add_u32 v2, v2, 2, s34
	v_lshl_add_u32 v3, v3, 2, s34
	ds_add_u32 v2, v213
	ds_add_u32 v3, v213
	v_cmp_eq_u32_e32 vcc, 0, v50
	v_cmp_eq_u32_e64 s[98:99], 0, v49
	v_lshrrev_b32_e32 v2, 20, v50
	v_lshrrev_b32_e32 v3, 20, v49
	v_cndmask_b32_e32 v2, v2, v221, vcc
	v_cndmask_b32_e64 v3, v3, v221, s[98:99]
	v_lshl_add_u32 v2, v2, 2, s34
	v_lshl_add_u32 v3, v3, 2, s34
	ds_add_u32 v2, v213
	ds_add_u32 v3, v213
	v_cndmask_b32_e64 v2, 0, 1, s[12:13]
	v_cmp_ne_u32_e64 s[10:11], 1, v2
	s_andn2_b64 vcc, exec, s[12:13]
	s_cbranch_vccnz .LBB0_489
.LBB0_519:
	s_waitcnt lgkmcnt(14)
	v_cmp_eq_u32_e32 vcc, 0, v52
	v_cmp_eq_u32_e64 s[98:99], 0, v51
	v_lshrrev_b32_e32 v2, 20, v52
	v_lshrrev_b32_e32 v3, 20, v51
	v_cndmask_b32_e32 v2, v2, v221, vcc
	v_cndmask_b32_e64 v3, v3, v221, s[98:99]
	v_lshl_add_u32 v2, v2, 2, s34
	v_lshl_add_u32 v3, v3, 2, s34
	ds_add_u32 v2, v213
	ds_add_u32 v3, v213
	v_cmp_eq_u32_e32 vcc, 0, v54
	v_cmp_eq_u32_e64 s[98:99], 0, v53
	v_lshrrev_b32_e32 v2, 20, v54
	v_lshrrev_b32_e32 v3, 20, v53
	v_cndmask_b32_e32 v2, v2, v221, vcc
	v_cndmask_b32_e64 v3, v3, v221, s[98:99]
	v_lshl_add_u32 v2, v2, 2, s34
	v_lshl_add_u32 v3, v3, 2, s34
	ds_add_u32 v2, v213
	ds_add_u32 v3, v213
	v_cmp_eq_u32_e32 vcc, 0, v56
	v_cmp_eq_u32_e64 s[98:99], 0, v55
	v_lshrrev_b32_e32 v2, 20, v56
	v_lshrrev_b32_e32 v3, 20, v55
	v_cndmask_b32_e32 v2, v2, v221, vcc
	v_cndmask_b32_e64 v3, v3, v221, s[98:99]
	v_lshl_add_u32 v2, v2, 2, s34
	v_lshl_add_u32 v3, v3, 2, s34
	ds_add_u32 v2, v213
	ds_add_u32 v3, v213
	v_cmp_eq_u32_e32 vcc, 0, v58
	v_cmp_eq_u32_e64 s[98:99], 0, v57
	v_lshrrev_b32_e32 v2, 20, v58
	v_lshrrev_b32_e32 v3, 20, v57
	v_cndmask_b32_e32 v2, v2, v221, vcc
	v_cndmask_b32_e64 v3, v3, v221, s[98:99]
	v_lshl_add_u32 v2, v2, 2, s34
	v_lshl_add_u32 v3, v3, 2, s34
	ds_add_u32 v2, v213
	ds_add_u32 v3, v213
	v_cndmask_b32_e64 v2, 0, 1, s[16:17]
	v_cmp_ne_u32_e64 s[12:13], 1, v2
	s_andn2_b64 vcc, exec, s[16:17]
	s_cbranch_vccz .LBB0_490
	s_branch .LBB0_491
